# cooperative grid-sync poll loop: s_sleep 6 instead of s_sleep 1 between polls of the single barrier word (less contention with the 256 arrival atomics)
# speedup vs baseline: 1.0089x; 1.0037x over previous
; __global__ void __launch_bounds__(NTHREADS, 2) fwd_megakernel(Args args) {
;     ...
;     grid.sync();
.LBB0_54:
	s_sleep 6
	global_load_dword v2, v0, s[4:5] offset:32 sc1
	s_waitcnt vmcnt(0)
	v_and_b32_e32 v2, 0xffff0000, v2
	v_cmp_ne_u32_e32 vcc, v2, v1
	s_or_b64 s[6:7], vcc, s[6:7]
	s_andn2_b64 exec, exec, s[6:7]
	s_cbranch_execnz .LBB0_54
